# attention: per-tile running-max check replaced by fixed tile-0 reference + post-item overflow check (l<2^100, O finite) with workgroup-wide redo through the rescaling loop; forced-redo path validated
# speedup vs baseline: 1.2234x; 1.0172x over previous
; DI void phase_attn(const Params& p, int layer, char* smem) {
;     ...
;   for (int it = blockIdx.x; it < n_lat + n_ctx; it += gridDim.x) {
;     int combo, qb;
;     if (it < n_lat) { int xc = it & 7, j = it >> 3; combo = (j >> 5) * 8 + xc; qb = 2 + (j & 31); }
;     else { int r = it - n_lat; combo = r >> 1; qb = r & 1; }
;     const int type = combo / 48, bh = combo % 48;
;     attn_dispatch(p, type, bh / 6, bh % 6, qb, smem);
.Lat_item:
	s_cmp_lt_u32 s52, 0xc00
	s_cbranch_scc0 .Lat_done
	s_and_b32 s0, s52, 7
	s_lshr_b32 s1, s52, 3
	s_lshr_b32 s10, s1, 5
	s_lshl_b32 s10, s10, 3
	s_add_u32 s10, s10, s0
	s_and_b32 s1, s1, 31
	s_add_u32 s1, s1, 2
	s_lshl_b32 s56, s1, 7
	s_mov_b32 s53, 0
	s_mov_b32 s74, 0
	s_cmp_ge_u32 s10, 48
	s_cbranch_scc0 .Lat_ty_1
	s_mov_b32 s53, 1
	s_sub_u32 s10, s10, 48

; template <int DQK>
; DI void attn_item(const bf16_t* __restrict__ Q, const bf16_t* __restrict__ Kp, const bf16_t* __restrict__ Vt, int q0, int nkeys,
;                   bf16_t* __restrict__ mix, int colbase, int b, char* smem) {
;     ...
;   bf16x8 qf[NSTEP];
;   {
;     const bf16_t* qr = Q + (size_t)(q0 + wave * 32 + r) * DQK + 8 * h;
; #pragma unroll
;     for (int s = 0; s < NSTEP; ++s) qf[s] = *(const bf16x8*)(qr + 16 * s);
;   }
;   const int kid0 = tid, kid1 = tid + 256, kid2 = tid + 512;
;   const int kgo0 = (kid0 / KCH) * DQK + (kid0 % KCH) * 8, kgo1 = (kid1 / KCH) * DQK + (kid1 % KCH) * 8, kgo2 = (kid2 / KCH) * DQK + (kid2 % KCH) * 8;
;   const int kso0 = (kid0 / KCH) * KROW + (kid0 % KCH) * 8, kso1 = (kid1 / KCH) * KROW + (kid1 % KCH) * 8, kso2 = (kid2 / KCH) * KROW + (kid2 % KCH) * 8;
;   const int vrow0 = tid >> 3, vcc = (tid & 7) * 8;
;   const bf16_t* Vg0 = Vt + (size_t)vrow0 * NKEY + vcc;
;   const bf16_t* Vg1 = Vt + (size_t)(vrow0 + 32) * NKEY + vcc;
;   const int vso0 = vrow0 * VROW + vcc, vso1 = (vrow0 + 32) * VROW + vcc;
;   uint4 pk0, pk1, pk2, pv0, pv1, qk0, qk1, qk2, qv0, qv1;
;   pk2 = make_uint4(0, 0, 0, 0); qk2 = pk2;
;     ...
;   f32x16 o0, o1;
; #pragma unroll
;   for (int i = 0; i < 16; ++i) { o0[i] = 0.f; o1[i] = 0.f; }
;   float m = -1e30f, l = 0.f;
.Lat_redo_g:
	s_barrier
	global_load_dwordx4 v[112:115], v251, s[58:59] offset:0
	global_load_dwordx4 v[116:119], v251, s[58:59] offset:32
	global_load_dwordx4 v[120:123], v251, s[58:59] offset:64
	global_load_dwordx4 v[124:127], v251, s[58:59] offset:96
	s_mov_b32 s1, 0
	s_min_u32 s0, s1, 67
	s_mul_i32 s0, s0, 0x2000
	s_add_u32 s64, s60, s0
	s_addc_u32 s65, s61, 0
	s_min_u32 s0, s1, 67
	s_lshl_b32 s0, s0, 7
	s_add_u32 s66, s62, s0
	s_addc_u32 s67, s63, 0
	global_load_dwordx4 v[176:179], v246, s[64:65]
	global_load_dwordx4 v[180:183], v247, s[64:65]
	global_load_dwordx4 v[212:215], v249, s[66:67]
	global_load_dwordx4 v[216:219], v250, s[66:67]
	s_waitcnt vmcnt(0)
	ds_write_b128 v241, v[176:179] offset:0
	ds_write_b128 v242, v[180:183] offset:0
	ds_write_b64 v244, v[212:213] offset:18432
	ds_write_b64 v244, v[214:215] offset:18440
	ds_write_b64 v245, v[216:217] offset:18432
	ds_write_b64 v245, v[218:219] offset:18440
	s_mov_b32 s1, 1
	s_min_u32 s0, s1, 67
	s_mul_i32 s0, s0, 0x2000
	s_add_u32 s64, s60, s0
	s_addc_u32 s65, s61, 0
	s_min_u32 s0, s1, 67
	s_lshl_b32 s0, s0, 7
	s_add_u32 s66, s62, s0
	s_addc_u32 s67, s63, 0
	global_load_dwordx4 v[176:179], v246, s[64:65]
	global_load_dwordx4 v[180:183], v247, s[64:65]
	s_waitcnt vmcnt(0)
	ds_write_b128 v241, v[176:179] offset:9216
	ds_write_b128 v242, v[180:183] offset:9216
	s_mov_b32 s1, 2
	s_mov_b32 s10, 1
	s_min_u32 s0, s1, 67
	s_mul_i32 s0, s0, 0x2000
	s_add_u32 s64, s60, s0
	s_addc_u32 s65, s61, 0
	s_min_u32 s0, s10, 67
	s_lshl_b32 s0, s0, 7
	s_add_u32 s66, s62, s0
	s_addc_u32 s67, s63, 0
	global_load_dwordx4 v[176:179], v246, s[64:65]
	global_load_dwordx4 v[180:183], v247, s[64:65]
	global_load_dwordx4 v[212:215], v249, s[66:67]
	global_load_dwordx4 v[216:219], v250, s[66:67]
	v_mov_b32_e32 v0, 0
	v_mov_b32_e32 v1, 0
	v_mov_b32_e32 v2, 0
	v_mov_b32_e32 v3, 0
	v_mov_b32_e32 v4, 0
	v_mov_b32_e32 v5, 0
	v_mov_b32_e32 v6, 0
	v_mov_b32_e32 v7, 0
	v_mov_b32_e32 v8, 0
	v_mov_b32_e32 v9, 0
	v_mov_b32_e32 v10, 0
	v_mov_b32_e32 v11, 0
	v_mov_b32_e32 v12, 0
	v_mov_b32_e32 v13, 0
	v_mov_b32_e32 v14, 0
	v_mov_b32_e32 v15, 0
	v_mov_b32_e32 v16, 0
	v_mov_b32_e32 v17, 0
	v_mov_b32_e32 v18, 0
	v_mov_b32_e32 v19, 0
	v_mov_b32_e32 v20, 0
	v_mov_b32_e32 v21, 0
	v_mov_b32_e32 v22, 0
	v_mov_b32_e32 v23, 0
	v_mov_b32_e32 v24, 0
	v_mov_b32_e32 v25, 0
	v_mov_b32_e32 v26, 0
	v_mov_b32_e32 v27, 0
	v_mov_b32_e32 v28, 0
	v_mov_b32_e32 v29, 0
	v_mov_b32_e32 v30, 0
	v_mov_b32_e32 v31, 0
	v_mov_b32_e32 v221, 0
	s_waitcnt lgkmcnt(0)
	s_barrier
	ds_read_b128 v[144:147], v238 offset:0
	ds_read_b128 v[148:151], v238 offset:4608
	ds_read_b128 v[152:155], v238 offset:32
	ds_read_b128 v[156:159], v238 offset:4640
	s_waitcnt lgkmcnt(3)
	v_mfma_f32_32x32x16_bf16 v[32:47], v[144:147], v[112:115], 0
	ds_read_b128 v[144:147], v238 offset:64
	s_waitcnt lgkmcnt(3)
	v_mfma_f32_32x32x16_bf16 v[48:63], v[148:151], v[112:115], 0
	ds_read_b128 v[148:151], v238 offset:4672
	s_waitcnt lgkmcnt(3)
	v_mfma_f32_32x32x16_bf16 v[32:47], v[152:155], v[116:119], v[32:47]
	ds_read_b128 v[152:155], v238 offset:96
	s_waitcnt lgkmcnt(3)
	v_mfma_f32_32x32x16_bf16 v[48:63], v[156:159], v[116:119], v[48:63]
	ds_read_b128 v[156:159], v238 offset:4704
	s_waitcnt lgkmcnt(3)
	v_mfma_f32_32x32x16_bf16 v[32:47], v[144:147], v[120:123], v[32:47]
	s_waitcnt lgkmcnt(2)
	v_mfma_f32_32x32x16_bf16 v[48:63], v[148:151], v[120:123], v[48:63]
	s_waitcnt lgkmcnt(1)
	v_mfma_f32_32x32x16_bf16 v[32:47], v[152:155], v[124:127], v[32:47]
	s_waitcnt lgkmcnt(0)
	v_mfma_f32_32x32x16_bf16 v[48:63], v[156:159], v[124:127], v[48:63]
	s_waitcnt lgkmcnt(0)
	s_barrier
	s_nop 7
	s_nop 3
	v_max3_f32 v223, v32, v33, v34
	v_max3_f32 v224, v40, v41, v42
	v_max3_f32 v225, v48, v49, v50
	v_max3_f32 v226, v56, v57, v58
	v_max3_f32 v223, v223, v35, v36
	v_max3_f32 v224, v224, v43, v44
	v_max3_f32 v225, v225, v51, v52
	v_max3_f32 v226, v226, v59, v60
	v_max3_f32 v223, v223, v37, v38
	v_max3_f32 v224, v224, v45, v46
	v_max3_f32 v225, v225, v53, v54
	v_max3_f32 v226, v226, v61, v62
	v_max_f32_e32 v223, v223, v39
	v_max_f32_e32 v224, v224, v47
	v_max_f32_e32 v225, v225, v55
	v_max_f32_e32 v226, v226, v63
	v_max3_f32 v222, v223, v224, v225
	v_max_f32_e32 v222, v222, v226
	v_mov_b32_e32 v227, v222
	s_nop 1
	v_permlane32_swap_b32_e32 v222, v227
	v_max_f32_e32 v222, v222, v227
	v_sub_f32_e32 v32, v32, v222
	v_sub_f32_e32 v33, v33, v222
	v_sub_f32_e32 v34, v34, v222
	v_sub_f32_e32 v35, v35, v222
	v_sub_f32_e32 v36, v36, v222
	v_sub_f32_e32 v37, v37, v222
	v_sub_f32_e32 v38, v38, v222
	v_sub_f32_e32 v39, v39, v222
	v_sub_f32_e32 v40, v40, v222
	v_sub_f32_e32 v41, v41, v222
	v_sub_f32_e32 v42, v42, v222
	v_sub_f32_e32 v43, v43, v222
	v_sub_f32_e32 v44, v44, v222
	v_sub_f32_e32 v45, v45, v222
	v_sub_f32_e32 v46, v46, v222
	v_sub_f32_e32 v47, v47, v222
	v_sub_f32_e32 v48, v48, v222
	v_sub_f32_e32 v49, v49, v222
	v_sub_f32_e32 v50, v50, v222
	v_sub_f32_e32 v51, v51, v222
	v_sub_f32_e32 v52, v52, v222
	v_sub_f32_e32 v53, v53, v222
	v_sub_f32_e32 v54, v54, v222
	v_sub_f32_e32 v55, v55, v222
	v_sub_f32_e32 v56, v56, v222
	v_sub_f32_e32 v57, v57, v222
	v_sub_f32_e32 v58, v58, v222
	v_sub_f32_e32 v59, v59, v222
	v_sub_f32_e32 v60, v60, v222
	v_sub_f32_e32 v61, v61, v222
	v_sub_f32_e32 v62, v62, v222
	v_sub_f32_e32 v63, v63, v222
	v_sub_f32_e32 v160, 0, v222
	v_sub_f32_e32 v161, 0, v222
	v_sub_f32_e32 v162, 0, v222
	v_sub_f32_e32 v163, 0, v222
	v_sub_f32_e32 v164, 0, v222
	v_sub_f32_e32 v165, 0, v222
	v_sub_f32_e32 v166, 0, v222
	v_sub_f32_e32 v167, 0, v222
	v_sub_f32_e32 v168, 0, v222
	v_sub_f32_e32 v169, 0, v222
	v_sub_f32_e32 v170, 0, v222
	v_sub_f32_e32 v171, 0, v222
	v_sub_f32_e32 v172, 0, v222
	v_sub_f32_e32 v173, 0, v222
	v_sub_f32_e32 v174, 0, v222
	v_sub_f32_e32 v175, 0, v222
	s_mov_b32 s69, 0
	s_mov_b32 s68, 0
	s_cmp_eq_u32 s74, 1
	s_cbranch_scc1 .Lat_safe_g
; template <int DQK>
; DI void attn_item(const bf16_t* __restrict__ Q, const bf16_t* __restrict__ Kp, const bf16_t* __restrict__ Vt, int q0, int nkeys,
;                   bf16_t* __restrict__ mix, int colbase, int b, char* smem) {
;     ...
;   const int nt = nkeys >> 6;
;   A_LOAD(p, 0)
;   A_LOAD(q, 64)
;   A_WRITE(p, 0)
;   __syncthreads();
;   if (nt > 2) A_LOAD(p, 128)
;   for (int kt = 0; kt < nt; kt += 2) {
;     A_TILE(0)
;     A_WRITE(q, 1)
;     __syncthreads();
;     if (kt + 3 < nt) A_LOAD(q, (kt + 3) << 6)
;     A_TILE(1)
;     if (kt + 2 < nt) A_WRITE(p, 0)
;     __syncthreads();
.Lat_floop_g:
	s_waitcnt vmcnt(0)
	ds_write_b128 v241, v[176:179] offset:0
	ds_write_b128 v242, v[180:183] offset:0
	ds_write_b64 v244, v[212:213] offset:27136
	ds_write_b64 v244, v[214:215] offset:27144
	ds_write_b64 v245, v[216:217] offset:27136
	ds_write_b64 v245, v[218:219] offset:27144
	s_add_u32 s1, s68, 3
	s_add_u32 s10, s68, 2
	s_min_u32 s0, s1, 67
	s_mul_i32 s0, s0, 0x2000
	s_add_u32 s64, s60, s0
	s_addc_u32 s65, s61, 0
	s_min_u32 s0, s10, 67
	s_lshl_b32 s0, s0, 7
	s_add_u32 s66, s62, s0
	s_addc_u32 s67, s63, 0
	global_load_dwordx4 v[176:179], v246, s[64:65]
	global_load_dwordx4 v[180:183], v247, s[64:65]
	global_load_dwordx4 v[212:215], v249, s[66:67]
	global_load_dwordx4 v[216:219], v250, s[66:67]
	ds_read_b128 v[144:147], v238 offset:9216
	ds_read_b128 v[148:151], v238 offset:13824
	ds_read_b128 v[152:155], v238 offset:9248
	ds_read_b128 v[156:159], v238 offset:13856
	v_exp_f32_e32 v32, v32
	v_exp_f32_e32 v33, v33
	v_exp_f32_e32 v34, v34
	s_waitcnt lgkmcnt(3)
	v_mfma_f32_32x32x16_bf16 v[64:79], v[144:147], v[112:115], v[160:175]
	ds_read_b128 v[144:147], v238 offset:9280
	v_exp_f32_e32 v35, v35
	v_exp_f32_e32 v36, v36
	v_exp_f32_e32 v37, v37
	s_waitcnt lgkmcnt(3)
	v_mfma_f32_32x32x16_bf16 v[80:95], v[148:151], v[112:115], v[160:175]
	ds_read_b128 v[148:151], v238 offset:13888
	v_exp_f32_e32 v38, v38
	v_exp_f32_e32 v39, v39
	v_exp_f32_e32 v40, v40
	s_waitcnt lgkmcnt(3)
	v_mfma_f32_32x32x16_bf16 v[64:79], v[152:155], v[116:119], v[64:79]
	ds_read_b128 v[152:155], v238 offset:9312
	v_exp_f32_e32 v41, v41
	v_exp_f32_e32 v42, v42
	v_exp_f32_e32 v43, v43
	s_waitcnt lgkmcnt(3)
	v_mfma_f32_32x32x16_bf16 v[80:95], v[156:159], v[116:119], v[80:95]
	ds_read_b128 v[156:159], v238 offset:13920
	v_exp_f32_e32 v44, v44
	v_exp_f32_e32 v45, v45
	v_exp_f32_e32 v46, v46
	s_waitcnt lgkmcnt(3)
	v_mfma_f32_32x32x16_bf16 v[64:79], v[144:147], v[120:123], v[64:79]
	v_exp_f32_e32 v47, v47
	v_exp_f32_e32 v48, v48
	v_exp_f32_e32 v49, v49
	s_waitcnt lgkmcnt(2)
	v_mfma_f32_32x32x16_bf16 v[80:95], v[148:151], v[120:123], v[80:95]
	v_exp_f32_e32 v50, v50
	v_exp_f32_e32 v51, v51
	v_exp_f32_e32 v52, v52
	s_waitcnt lgkmcnt(1)
	v_mfma_f32_32x32x16_bf16 v[64:79], v[152:155], v[124:127], v[64:79]
	v_exp_f32_e32 v53, v53
	v_exp_f32_e32 v54, v54
	v_exp_f32_e32 v55, v55
	s_waitcnt lgkmcnt(0)
	v_mfma_f32_32x32x16_bf16 v[80:95], v[156:159], v[124:127], v[80:95]
	v_exp_f32_e32 v56, v56
	v_exp_f32_e32 v57, v57
	v_exp_f32_e32 v58, v58
	v_exp_f32_e32 v59, v59
	v_exp_f32_e32 v60, v60
	v_exp_f32_e32 v61, v61
	v_exp_f32_e32 v62, v62
	v_exp_f32_e32 v63, v63
	v_add_u32_e32 v223, 0x4800, v239
	v_add_u32_e32 v224, 0x4800, v240
	ds_read2_b64 v[144:147], v223 offset0:0 offset1:2
	ds_read2_b64 v[148:151], v224 offset0:0 offset1:2
	ds_read2_b64 v[152:155], v223 offset0:4 offset1:6
	ds_read2_b64 v[156:159], v224 offset0:4 offset1:6
	v_cvt_pk_bf16_f32 v96, v32, v33
	v_cvt_pk_bf16_f32 v97, v34, v35
	v_cvt_pk_bf16_f32 v98, v36, v37
	v_cvt_pk_bf16_f32 v99, v38, v39
	v_add_f32_e32 v231, v32, v36
	v_add_f32_e32 v232, v33, v37
	v_add_f32_e32 v233, v34, v38
	v_add_f32_e32 v237, v35, v39
	s_waitcnt lgkmcnt(3)
	v_mfma_f32_32x32x16_bf16 v[0:15], v[144:147], v[96:99], v[0:15]
	ds_read2_b64 v[144:147], v223 offset0:8 offset1:10
	s_waitcnt lgkmcnt(3)
	v_mfma_f32_32x32x16_bf16 v[16:31], v[148:151], v[96:99], v[16:31]
	ds_read2_b64 v[148:151], v224 offset0:8 offset1:10
	v_cvt_pk_bf16_f32 v100, v40, v41
	v_cvt_pk_bf16_f32 v101, v42, v43
	v_cvt_pk_bf16_f32 v102, v44, v45
	v_cvt_pk_bf16_f32 v103, v46, v47
	v_add_f32_e32 v231, v231, v40
	v_add_f32_e32 v232, v232, v41
	v_add_f32_e32 v233, v233, v42
	v_add_f32_e32 v237, v237, v43
	v_add_f32_e32 v231, v231, v44
	v_add_f32_e32 v232, v232, v45
	v_add_f32_e32 v233, v233, v46
	v_add_f32_e32 v237, v237, v47
	s_waitcnt lgkmcnt(3)
	v_mfma_f32_32x32x16_bf16 v[0:15], v[152:155], v[100:103], v[0:15]
	ds_read2_b64 v[152:155], v223 offset0:12 offset1:14
	s_waitcnt lgkmcnt(3)
	v_mfma_f32_32x32x16_bf16 v[16:31], v[156:159], v[100:103], v[16:31]
	ds_read2_b64 v[156:159], v224 offset0:12 offset1:14
	v_cvt_pk_bf16_f32 v104, v48, v49
	v_cvt_pk_bf16_f32 v105, v50, v51
	v_cvt_pk_bf16_f32 v106, v52, v53
	v_cvt_pk_bf16_f32 v107, v54, v55
	v_add_f32_e32 v231, v231, v48
	v_add_f32_e32 v232, v232, v49
	v_add_f32_e32 v233, v233, v50
	v_add_f32_e32 v237, v237, v51
	v_add_f32_e32 v231, v231, v52
	v_add_f32_e32 v232, v232, v53
	v_add_f32_e32 v233, v233, v54
	v_add_f32_e32 v237, v237, v55
	s_waitcnt lgkmcnt(3)
	v_mfma_f32_32x32x16_bf16 v[0:15], v[144:147], v[104:107], v[0:15]
	s_waitcnt lgkmcnt(2)
	v_mfma_f32_32x32x16_bf16 v[16:31], v[148:151], v[104:107], v[16:31]
	v_cvt_pk_bf16_f32 v108, v56, v57
	v_cvt_pk_bf16_f32 v109, v58, v59
	v_cvt_pk_bf16_f32 v110, v60, v61
	v_cvt_pk_bf16_f32 v111, v62, v63
	v_add_f32_e32 v231, v231, v56
	v_add_f32_e32 v232, v232, v57
	v_add_f32_e32 v233, v233, v58
	v_add_f32_e32 v237, v237, v59
	v_add_f32_e32 v231, v231, v60
	v_add_f32_e32 v232, v232, v61
	v_add_f32_e32 v233, v233, v62
	v_add_f32_e32 v237, v237, v63
	s_waitcnt lgkmcnt(1)
	v_mfma_f32_32x32x16_bf16 v[0:15], v[152:155], v[108:111], v[0:15]
	s_waitcnt lgkmcnt(0)
	v_mfma_f32_32x32x16_bf16 v[16:31], v[156:159], v[108:111], v[16:31]
	v_add_f32_e32 v231, v231, v232
	v_add_f32_e32 v233, v233, v237
	v_add_f32_e32 v231, v231, v233
	v_add_f32_e32 v221, v221, v231
	s_add_u32 s68, s68, 1
	s_waitcnt lgkmcnt(0)
	s_barrier
; DI float xhalf_sum(float x) { auto r = __builtin_amdgcn_permlane32_swap(__float_as_uint(x), __float_as_uint(x), false, false); return __uint_as_float(r[0]) + __uint_as_float(r[1]); }
; template <int DQK>
; DI void attn_item(const bf16_t* __restrict__ Q, const bf16_t* __restrict__ Kp, const bf16_t* __restrict__ Vt, int q0, int nkeys,
;                   bf16_t* __restrict__ mix, int colbase, int b, char* smem) {
;     ...
;   const int nt = nkeys >> 6;
;   A_LOAD(p, 0)
;   A_LOAD(q, 64)
;   A_WRITE(p, 0)
;   __syncthreads();
;   if (nt > 2) A_LOAD(p, 128)
;   for (int kt = 0; kt < nt; kt += 2) {
;     A_TILE(0)
;     A_WRITE(q, 1)
;     __syncthreads();
;     if (kt + 3 < nt) A_LOAD(q, (kt + 3) << 6)
;     A_TILE(1)
;     if (kt + 2 < nt) A_WRITE(p, 0)
;     __syncthreads();
;     if (kt + 4 < nt) A_LOAD(p, (kt + 4) << 6)
;   }
;     ...
;   l = xhalf_sum(l);
;   const float inv = 1.0f / l;
	s_waitcnt vmcnt(0)
	ds_write_b128 v241, v[176:179] offset:9216
	ds_write_b128 v242, v[180:183] offset:9216
	ds_write_b64 v244, v[212:213] offset:18432
	ds_write_b64 v244, v[214:215] offset:18440
	ds_write_b64 v245, v[216:217] offset:18432
	ds_write_b64 v245, v[218:219] offset:18440
	s_add_u32 s1, s68, 3
	s_add_u32 s10, s68, 2
	s_min_u32 s0, s1, 67
	s_mul_i32 s0, s0, 0x2000
	s_add_u32 s64, s60, s0
	s_addc_u32 s65, s61, 0
	s_min_u32 s0, s10, 67
	s_lshl_b32 s0, s0, 7
	s_add_u32 s66, s62, s0
	s_addc_u32 s67, s63, 0
	global_load_dwordx4 v[176:179], v246, s[64:65]
	global_load_dwordx4 v[180:183], v247, s[64:65]
	global_load_dwordx4 v[212:215], v249, s[66:67]
	global_load_dwordx4 v[216:219], v250, s[66:67]
	ds_read_b128 v[144:147], v238 offset:0
	ds_read_b128 v[148:151], v238 offset:4608
	ds_read_b128 v[152:155], v238 offset:32
	ds_read_b128 v[156:159], v238 offset:4640
	v_exp_f32_e32 v64, v64
	v_exp_f32_e32 v65, v65
	v_exp_f32_e32 v66, v66
	s_waitcnt lgkmcnt(3)
	v_mfma_f32_32x32x16_bf16 v[32:47], v[144:147], v[112:115], v[160:175]
	ds_read_b128 v[144:147], v238 offset:64
	v_exp_f32_e32 v67, v67
	v_exp_f32_e32 v68, v68
	v_exp_f32_e32 v69, v69
	s_waitcnt lgkmcnt(3)
	v_mfma_f32_32x32x16_bf16 v[48:63], v[148:151], v[112:115], v[160:175]
	ds_read_b128 v[148:151], v238 offset:4672
	v_exp_f32_e32 v70, v70
	v_exp_f32_e32 v71, v71
	v_exp_f32_e32 v72, v72
	s_waitcnt lgkmcnt(3)
	v_mfma_f32_32x32x16_bf16 v[32:47], v[152:155], v[116:119], v[32:47]
	ds_read_b128 v[152:155], v238 offset:96
	v_exp_f32_e32 v73, v73
	v_exp_f32_e32 v74, v74
	v_exp_f32_e32 v75, v75
	s_waitcnt lgkmcnt(3)
	v_mfma_f32_32x32x16_bf16 v[48:63], v[156:159], v[116:119], v[48:63]
	ds_read_b128 v[156:159], v238 offset:4704
	v_exp_f32_e32 v76, v76
	v_exp_f32_e32 v77, v77
	v_exp_f32_e32 v78, v78
	s_waitcnt lgkmcnt(3)
	v_mfma_f32_32x32x16_bf16 v[32:47], v[144:147], v[120:123], v[32:47]
	v_exp_f32_e32 v79, v79
	v_exp_f32_e32 v80, v80
	v_exp_f32_e32 v81, v81
	s_waitcnt lgkmcnt(2)
	v_mfma_f32_32x32x16_bf16 v[48:63], v[148:151], v[120:123], v[48:63]
	v_exp_f32_e32 v82, v82
	v_exp_f32_e32 v83, v83
	v_exp_f32_e32 v84, v84
	s_waitcnt lgkmcnt(1)
	v_mfma_f32_32x32x16_bf16 v[32:47], v[152:155], v[124:127], v[32:47]
	v_exp_f32_e32 v85, v85
	v_exp_f32_e32 v86, v86
	v_exp_f32_e32 v87, v87
	s_waitcnt lgkmcnt(0)
	v_mfma_f32_32x32x16_bf16 v[48:63], v[156:159], v[124:127], v[48:63]
	v_exp_f32_e32 v88, v88
	v_exp_f32_e32 v89, v89
	v_exp_f32_e32 v90, v90
	v_exp_f32_e32 v91, v91
	v_exp_f32_e32 v92, v92
	v_exp_f32_e32 v93, v93
	v_exp_f32_e32 v94, v94
	v_exp_f32_e32 v95, v95
	v_add_u32_e32 v223, 0x6a00, v239
	v_add_u32_e32 v224, 0x6a00, v240
	ds_read2_b64 v[144:147], v223 offset0:0 offset1:2
	ds_read2_b64 v[148:151], v224 offset0:0 offset1:2
	ds_read2_b64 v[152:155], v223 offset0:4 offset1:6
	ds_read2_b64 v[156:159], v224 offset0:4 offset1:6
	v_cvt_pk_bf16_f32 v96, v64, v65
	v_cvt_pk_bf16_f32 v97, v66, v67
	v_cvt_pk_bf16_f32 v98, v68, v69
	v_cvt_pk_bf16_f32 v99, v70, v71
	v_add_f32_e32 v231, v64, v68
	v_add_f32_e32 v232, v65, v69
	v_add_f32_e32 v233, v66, v70
	v_add_f32_e32 v237, v67, v71
	s_waitcnt lgkmcnt(3)
	v_mfma_f32_32x32x16_bf16 v[0:15], v[144:147], v[96:99], v[0:15]
	ds_read2_b64 v[144:147], v223 offset0:8 offset1:10
	s_waitcnt lgkmcnt(3)
	v_mfma_f32_32x32x16_bf16 v[16:31], v[148:151], v[96:99], v[16:31]
	ds_read2_b64 v[148:151], v224 offset0:8 offset1:10
	v_cvt_pk_bf16_f32 v100, v72, v73
	v_cvt_pk_bf16_f32 v101, v74, v75
	v_cvt_pk_bf16_f32 v102, v76, v77
	v_cvt_pk_bf16_f32 v103, v78, v79
	v_add_f32_e32 v231, v231, v72
	v_add_f32_e32 v232, v232, v73
	v_add_f32_e32 v233, v233, v74
	v_add_f32_e32 v237, v237, v75
	v_add_f32_e32 v231, v231, v76
	v_add_f32_e32 v232, v232, v77
	v_add_f32_e32 v233, v233, v78
	v_add_f32_e32 v237, v237, v79
	s_waitcnt lgkmcnt(3)
	v_mfma_f32_32x32x16_bf16 v[0:15], v[152:155], v[100:103], v[0:15]
	ds_read2_b64 v[152:155], v223 offset0:12 offset1:14
	s_waitcnt lgkmcnt(3)
	v_mfma_f32_32x32x16_bf16 v[16:31], v[156:159], v[100:103], v[16:31]
	ds_read2_b64 v[156:159], v224 offset0:12 offset1:14
	v_cvt_pk_bf16_f32 v104, v80, v81
	v_cvt_pk_bf16_f32 v105, v82, v83
	v_cvt_pk_bf16_f32 v106, v84, v85
	v_cvt_pk_bf16_f32 v107, v86, v87
	v_add_f32_e32 v231, v231, v80
	v_add_f32_e32 v232, v232, v81
	v_add_f32_e32 v233, v233, v82
	v_add_f32_e32 v237, v237, v83
	v_add_f32_e32 v231, v231, v84
	v_add_f32_e32 v232, v232, v85
	v_add_f32_e32 v233, v233, v86
	v_add_f32_e32 v237, v237, v87
	s_waitcnt lgkmcnt(3)
	v_mfma_f32_32x32x16_bf16 v[0:15], v[144:147], v[104:107], v[0:15]
	s_waitcnt lgkmcnt(2)
	v_mfma_f32_32x32x16_bf16 v[16:31], v[148:151], v[104:107], v[16:31]
	v_cvt_pk_bf16_f32 v108, v88, v89
	v_cvt_pk_bf16_f32 v109, v90, v91
	v_cvt_pk_bf16_f32 v110, v92, v93
	v_cvt_pk_bf16_f32 v111, v94, v95
	v_add_f32_e32 v231, v231, v88
	v_add_f32_e32 v232, v232, v89
	v_add_f32_e32 v233, v233, v90
	v_add_f32_e32 v237, v237, v91
	v_add_f32_e32 v231, v231, v92
	v_add_f32_e32 v232, v232, v93
	v_add_f32_e32 v233, v233, v94
	v_add_f32_e32 v237, v237, v95
	s_waitcnt lgkmcnt(1)
	v_mfma_f32_32x32x16_bf16 v[0:15], v[152:155], v[108:111], v[0:15]
	s_waitcnt lgkmcnt(0)
	v_mfma_f32_32x32x16_bf16 v[16:31], v[156:159], v[108:111], v[16:31]
	v_add_f32_e32 v231, v231, v232
	v_add_f32_e32 v233, v233, v237
	v_add_f32_e32 v231, v231, v233
	v_add_f32_e32 v221, v221, v231
	s_add_u32 s68, s68, 1
	s_waitcnt lgkmcnt(0)
	s_barrier
	s_cmp_lt_u32 s68, 68
	s_cbranch_scc1 .Lat_floop_g
	s_nop 7
	s_nop 7
	v_mov_b32_e32 v223, 0
	v_fmac_f32_e32 v223, 0, v0
	v_fmac_f32_e32 v223, 0, v1
	v_fmac_f32_e32 v223, 0, v2
	v_fmac_f32_e32 v223, 0, v3
	v_fmac_f32_e32 v223, 0, v4
	v_fmac_f32_e32 v223, 0, v5
	v_fmac_f32_e32 v223, 0, v6
	v_fmac_f32_e32 v223, 0, v7
	v_fmac_f32_e32 v223, 0, v8
	v_fmac_f32_e32 v223, 0, v9
	v_fmac_f32_e32 v223, 0, v10
	v_fmac_f32_e32 v223, 0, v11
	v_fmac_f32_e32 v223, 0, v12
	v_fmac_f32_e32 v223, 0, v13
	v_fmac_f32_e32 v223, 0, v14
	v_fmac_f32_e32 v223, 0, v15
	v_fmac_f32_e32 v223, 0, v16
	v_fmac_f32_e32 v223, 0, v17
	v_fmac_f32_e32 v223, 0, v18
	v_fmac_f32_e32 v223, 0, v19
	v_fmac_f32_e32 v223, 0, v20
	v_fmac_f32_e32 v223, 0, v21
	v_fmac_f32_e32 v223, 0, v22
	v_fmac_f32_e32 v223, 0, v23
	v_fmac_f32_e32 v223, 0, v24
	v_fmac_f32_e32 v223, 0, v25
	v_fmac_f32_e32 v223, 0, v26
	v_fmac_f32_e32 v223, 0, v27
	v_fmac_f32_e32 v223, 0, v28
	v_fmac_f32_e32 v223, 0, v29
	v_fmac_f32_e32 v223, 0, v30
	v_fmac_f32_e32 v223, 0, v31
	v_mov_b32_e32 v224, 0x71800000
	v_cmp_neq_f32_e32 vcc, 0, v223
	s_mov_b64 s[44:45], vcc
	v_cmp_nlt_f32_e32 vcc, v221, v224
	s_or_b64 vcc, vcc, s[44:45]
	s_cmp_lg_u64 vcc, 0
	s_cselect_b32 s0, 1, 0
	v_mov_b32_e32 v225, s0
	s_lshl_b32 s1, s57, 2
	s_add_u32 s1, s1, 0x10000
	v_mov_b32_e32 v226, s1
	v_mov_b32_e32 v227, 0x10000
	ds_write_b32 v226, v225
	s_waitcnt lgkmcnt(0)
	s_barrier
	ds_read_b128 v[144:147], v227
	s_waitcnt lgkmcnt(0)
	v_or3_b32 v225, v144, v145, v146
	v_or_b32_e32 v225, v225, v147
	s_nop 0
	v_readfirstlane_b32 s0, v225
	s_nop 3
	s_cmp_eq_u32 s0, 0
	s_cbranch_scc1 .Lat_epi_g
	s_mov_b32 s74, 1
	s_branch .Lat_redo_g
; template <int DQK>
; DI void attn_item(const bf16_t* __restrict__ Q, const bf16_t* __restrict__ Kp, const bf16_t* __restrict__ Vt, int q0, int nkeys,
;                   bf16_t* __restrict__ mix, int colbase, int b, char* smem) {
;     ...
;   for (int kt = 0; kt < nt; kt += 2) {
;     A_TILE(0)
;     A_WRITE(q, 1)
;     __syncthreads();
;     if (kt + 3 < nt) A_LOAD(q, (kt + 3) << 6)
.Lat_safe_g:
.Lat_loop_g:
	s_waitcnt vmcnt(0)
	ds_write_b128 v241, v[176:179] offset:0
	ds_write_b128 v242, v[180:183] offset:0
	ds_write_b64 v244, v[212:213] offset:27136
	ds_write_b64 v244, v[214:215] offset:27144
	ds_write_b64 v245, v[216:217] offset:27136
	ds_write_b64 v245, v[218:219] offset:27144
	s_add_u32 s1, s68, 3
	s_add_u32 s10, s68, 2
	s_min_u32 s0, s1, 67
	s_mul_i32 s0, s0, 0x2000
	s_add_u32 s64, s60, s0
	s_addc_u32 s65, s61, 0
	s_min_u32 s0, s10, 67
	s_lshl_b32 s0, s0, 7
	s_add_u32 s66, s62, s0
	s_addc_u32 s67, s63, 0
	global_load_dwordx4 v[176:179], v246, s[64:65]
	global_load_dwordx4 v[180:183], v247, s[64:65]
	global_load_dwordx4 v[212:215], v249, s[66:67]
	global_load_dwordx4 v[216:219], v250, s[66:67]
	s_cmp_eq_u32 s69, 0
	s_cbranch_scc1 .Lat_nopend_4
	v_sub_f32_e32 v32, v32, v220
	v_sub_f32_e32 v33, v33, v220
	v_sub_f32_e32 v34, v34, v220
	v_sub_f32_e32 v35, v35, v220
	v_sub_f32_e32 v36, v36, v220
	v_sub_f32_e32 v37, v37, v220
	v_sub_f32_e32 v38, v38, v220
	v_sub_f32_e32 v39, v39, v220
	v_sub_f32_e32 v40, v40, v220
	v_sub_f32_e32 v41, v41, v220
	v_sub_f32_e32 v42, v42, v220
	v_sub_f32_e32 v43, v43, v220
	v_sub_f32_e32 v44, v44, v220
	v_sub_f32_e32 v45, v45, v220
	v_sub_f32_e32 v46, v46, v220
	v_sub_f32_e32 v47, v47, v220
	v_sub_f32_e32 v48, v48, v220
	v_sub_f32_e32 v49, v49, v220
	v_sub_f32_e32 v50, v50, v220
	v_sub_f32_e32 v51, v51, v220
	v_sub_f32_e32 v52, v52, v220
	v_sub_f32_e32 v53, v53, v220
	v_sub_f32_e32 v54, v54, v220
	v_sub_f32_e32 v55, v55, v220
	v_sub_f32_e32 v56, v56, v220
	v_sub_f32_e32 v57, v57, v220
	v_sub_f32_e32 v58, v58, v220
	v_sub_f32_e32 v59, v59, v220
	v_sub_f32_e32 v60, v60, v220
	v_sub_f32_e32 v61, v61, v220
	v_sub_f32_e32 v62, v62, v220
	v_sub_f32_e32 v63, v63, v220
	s_mov_b32 s69, 0

; DI unsigned pack2(float lo, float hi) { f32x2_t v = {lo, hi}; bf16x2_t r = __builtin_convertvector(v, bf16x2_t); return __builtin_bit_cast(unsigned, r); }
; DI float xhalf_sum(float x) { auto r = __builtin_amdgcn_permlane32_swap(__float_as_uint(x), __float_as_uint(x), false, false); return __uint_as_float(r[0]) + __uint_as_float(r[1]); }
; template <int DQK>
; DI void attn_item(const bf16_t* __restrict__ Q, const bf16_t* __restrict__ Kp, const bf16_t* __restrict__ Vt, int q0, int nkeys,
;                   bf16_t* __restrict__ mix, int colbase, int b, char* smem) {
;     ...
;   l = xhalf_sum(l);
;   const float inv = 1.0f / l;
;   const int kp = q0 + wave * 32 + r;
;   bf16_t* orow = mix + (size_t)row_of(b, kp) * D + colbase;
; #pragma unroll
;   for (int g = 0; g < 4; ++g) {
;     uint2 w0, w1;
;     w0.x = pack2(o0[4 * g] * inv, o0[4 * g + 1] * inv); w0.y = pack2(o0[4 * g + 2] * inv, o0[4 * g + 3] * inv);
;     w1.x = pack2(o1[4 * g] * inv, o1[4 * g + 1] * inv); w1.y = pack2(o1[4 * g + 2] * inv, o1[4 * g + 3] * inv);
;     *(uint2*)(orow + 8 * g + 4 * h) = w0;
;     *(uint2*)(orow + 32 + 8 * g + 4 * h) = w1;
;   }
.Lat_epi_g:
	s_nop 7
	v_mov_b32_e32 v223, v221
	s_nop 1
	v_permlane32_swap_b32_e32 v221, v223
	v_add_f32_e32 v221, v221, v223
	v_rcp_f32_e32 v224, v221
	v_add_u32_e32 v226, 0x220000, v252
	s_nop 0
	v_mul_f32_e32 v96, v0, v224
	v_mul_f32_e32 v97, v1, v224
	v_mul_f32_e32 v98, v2, v224
	v_mul_f32_e32 v99, v3, v224
	v_cvt_pk_bf16_f32 v144, v96, v97
	v_cvt_pk_bf16_f32 v145, v98, v99
	global_store_dwordx2 v252, v[144:145], s[72:73] offset:0
	v_mul_f32_e32 v96, v16, v224
	v_mul_f32_e32 v97, v17, v224
	v_mul_f32_e32 v98, v18, v224
	v_mul_f32_e32 v99, v19, v224
	v_cvt_pk_bf16_f32 v146, v96, v97
	v_cvt_pk_bf16_f32 v147, v98, v99
	global_store_dwordx2 v226, v[146:147], s[72:73] offset:0
	v_mul_f32_e32 v96, v4, v224
	v_mul_f32_e32 v97, v5, v224
	v_mul_f32_e32 v98, v6, v224
	v_mul_f32_e32 v99, v7, v224
	v_cvt_pk_bf16_f32 v148, v96, v97
	v_cvt_pk_bf16_f32 v149, v98, v99
	global_store_dwordx2 v252, v[148:149], s[72:73] offset:16
	v_mul_f32_e32 v96, v20, v224
	v_mul_f32_e32 v97, v21, v224
	v_mul_f32_e32 v98, v22, v224
	v_mul_f32_e32 v99, v23, v224
	v_cvt_pk_bf16_f32 v150, v96, v97
	v_cvt_pk_bf16_f32 v151, v98, v99
	global_store_dwordx2 v226, v[150:151], s[72:73] offset:16
	v_mul_f32_e32 v96, v8, v224
	v_mul_f32_e32 v97, v9, v224
	v_mul_f32_e32 v98, v10, v224
	v_mul_f32_e32 v99, v11, v224
	v_cvt_pk_bf16_f32 v152, v96, v97
	v_cvt_pk_bf16_f32 v153, v98, v99
	global_store_dwordx2 v252, v[152:153], s[72:73] offset:32
	v_mul_f32_e32 v96, v24, v224
	v_mul_f32_e32 v97, v25, v224
	v_mul_f32_e32 v98, v26, v224
	v_mul_f32_e32 v99, v27, v224
	v_cvt_pk_bf16_f32 v154, v96, v97
	v_cvt_pk_bf16_f32 v155, v98, v99
	global_store_dwordx2 v226, v[154:155], s[72:73] offset:32
	v_mul_f32_e32 v96, v12, v224
	v_mul_f32_e32 v97, v13, v224
	v_mul_f32_e32 v98, v14, v224
	v_mul_f32_e32 v99, v15, v224
	v_cvt_pk_bf16_f32 v156, v96, v97
	v_cvt_pk_bf16_f32 v157, v98, v99
	global_store_dwordx2 v252, v[156:157], s[72:73] offset:48
	v_mul_f32_e32 v96, v28, v224
	v_mul_f32_e32 v97, v29, v224
	v_mul_f32_e32 v98, v30, v224
	v_mul_f32_e32 v99, v31, v224
	v_cvt_pk_bf16_f32 v158, v96, v97
	v_cvt_pk_bf16_f32 v159, v98, v99
	global_store_dwordx2 v226, v[158:159], s[72:73] offset:48
	s_branch .Lat_tyj_3

; template <int DQK>
; DI void attn_item(const bf16_t* __restrict__ Q, const bf16_t* __restrict__ Kp, const bf16_t* __restrict__ Vt, int q0, int nkeys,
;                   bf16_t* __restrict__ mix, int colbase, int b, char* smem) {
;     ...
;   bf16x8 qf[NSTEP];
;   {
;     const bf16_t* qr = Q + (size_t)(q0 + wave * 32 + r) * DQK + 8 * h;
; #pragma unroll
;     for (int s = 0; s < NSTEP; ++s) qf[s] = *(const bf16x8*)(qr + 16 * s);
;   }
;   const int kid0 = tid, kid1 = tid + 256, kid2 = tid + 512;
;   const int kgo0 = (kid0 / KCH) * DQK + (kid0 % KCH) * 8, kgo1 = (kid1 / KCH) * DQK + (kid1 % KCH) * 8, kgo2 = (kid2 / KCH) * DQK + (kid2 % KCH) * 8;
;   const int kso0 = (kid0 / KCH) * KROW + (kid0 % KCH) * 8, kso1 = (kid1 / KCH) * KROW + (kid1 % KCH) * 8, kso2 = (kid2 / KCH) * KROW + (kid2 % KCH) * 8;
;   const int vrow0 = tid >> 3, vcc = (tid & 7) * 8;
;   const bf16_t* Vg0 = Vt + (size_t)vrow0 * NKEY + vcc;
;   const bf16_t* Vg1 = Vt + (size_t)(vrow0 + 32) * NKEY + vcc;
;   const int vso0 = vrow0 * VROW + vcc, vso1 = (vrow0 + 32) * VROW + vcc;
;   uint4 pk0, pk1, pk2, pv0, pv1, qk0, qk1, qk2, qv0, qv1;
;   pk2 = make_uint4(0, 0, 0, 0); qk2 = pk2;
;     ...
;   f32x16 o0, o1;
; #pragma unroll
;   for (int i = 0; i < 16; ++i) { o0[i] = 0.f; o1[i] = 0.f; }
;   float m = -1e30f, l = 0.f;
.Lat_redo_m:
	s_barrier
	global_load_dwordx4 v[112:115], v251, s[58:59] offset:0
	global_load_dwordx4 v[116:119], v251, s[58:59] offset:32
	global_load_dwordx4 v[120:123], v251, s[58:59] offset:64
	global_load_dwordx4 v[124:127], v251, s[58:59] offset:96
	global_load_dwordx4 v[128:131], v251, s[58:59] offset:128
	global_load_dwordx4 v[132:135], v251, s[58:59] offset:160
	s_mov_b32 s1, 0
	s_min_u32 s0, s1, 67
	s_mul_i32 s0, s0, 0x3000
	s_add_u32 s64, s60, s0
	s_addc_u32 s65, s61, 0
	s_min_u32 s0, s1, 67
	s_lshl_b32 s0, s0, 7
	s_add_u32 s66, s62, s0
	s_addc_u32 s67, s63, 0
	global_load_dwordx4 v[176:179], v246, s[64:65]
	global_load_dwordx4 v[180:183], v247, s[64:65]
	global_load_dwordx4 v[184:187], v248, s[64:65]
	global_load_dwordx4 v[212:215], v249, s[66:67]
	global_load_dwordx4 v[216:219], v250, s[66:67]
	s_waitcnt vmcnt(0)
	ds_write_b128 v241, v[176:179] offset:0
	ds_write_b128 v242, v[180:183] offset:0
	ds_write_b128 v243, v[184:187] offset:0
	ds_write_b64 v244, v[212:213] offset:26624
	ds_write_b64 v244, v[214:215] offset:26632
	ds_write_b64 v245, v[216:217] offset:26624
	ds_write_b64 v245, v[218:219] offset:26632
	s_mov_b32 s1, 1
	s_min_u32 s0, s1, 67
	s_mul_i32 s0, s0, 0x3000
	s_add_u32 s64, s60, s0
	s_addc_u32 s65, s61, 0
	s_min_u32 s0, s1, 67
	s_lshl_b32 s0, s0, 7
	s_add_u32 s66, s62, s0
	s_addc_u32 s67, s63, 0
	global_load_dwordx4 v[176:179], v246, s[64:65]
	global_load_dwordx4 v[180:183], v247, s[64:65]
	global_load_dwordx4 v[184:187], v248, s[64:65]
	s_waitcnt vmcnt(0)
	ds_write_b128 v241, v[176:179] offset:13312
	ds_write_b128 v242, v[180:183] offset:13312
	ds_write_b128 v243, v[184:187] offset:13312
	s_mov_b32 s1, 2
	s_mov_b32 s10, 1
	s_min_u32 s0, s1, 67
	s_mul_i32 s0, s0, 0x3000
	s_add_u32 s64, s60, s0
	s_addc_u32 s65, s61, 0
	s_min_u32 s0, s10, 67
	s_lshl_b32 s0, s0, 7
	s_add_u32 s66, s62, s0
	s_addc_u32 s67, s63, 0
	global_load_dwordx4 v[176:179], v246, s[64:65]
	global_load_dwordx4 v[180:183], v247, s[64:65]
	global_load_dwordx4 v[184:187], v248, s[64:65]
	global_load_dwordx4 v[212:215], v249, s[66:67]
	global_load_dwordx4 v[216:219], v250, s[66:67]
	v_mov_b32_e32 v0, 0
	v_mov_b32_e32 v1, 0
	v_mov_b32_e32 v2, 0
	v_mov_b32_e32 v3, 0
	v_mov_b32_e32 v4, 0
	v_mov_b32_e32 v5, 0
	v_mov_b32_e32 v6, 0
	v_mov_b32_e32 v7, 0
	v_mov_b32_e32 v8, 0
	v_mov_b32_e32 v9, 0
	v_mov_b32_e32 v10, 0
	v_mov_b32_e32 v11, 0
	v_mov_b32_e32 v12, 0
	v_mov_b32_e32 v13, 0
	v_mov_b32_e32 v14, 0
	v_mov_b32_e32 v15, 0
	v_mov_b32_e32 v16, 0
	v_mov_b32_e32 v17, 0
	v_mov_b32_e32 v18, 0
	v_mov_b32_e32 v19, 0
	v_mov_b32_e32 v20, 0
	v_mov_b32_e32 v21, 0
	v_mov_b32_e32 v22, 0
	v_mov_b32_e32 v23, 0
	v_mov_b32_e32 v24, 0
	v_mov_b32_e32 v25, 0
	v_mov_b32_e32 v26, 0
	v_mov_b32_e32 v27, 0
	v_mov_b32_e32 v28, 0
	v_mov_b32_e32 v29, 0
	v_mov_b32_e32 v30, 0
	v_mov_b32_e32 v31, 0
	v_mov_b32_e32 v221, 0
	s_waitcnt lgkmcnt(0)
	s_barrier
	ds_read_b128 v[144:147], v238 offset:0
	ds_read_b128 v[148:151], v238 offset:6656
	ds_read_b128 v[152:155], v238 offset:32
	ds_read_b128 v[156:159], v238 offset:6688
	s_waitcnt lgkmcnt(3)
	v_mfma_f32_32x32x16_bf16 v[32:47], v[144:147], v[112:115], 0
	ds_read_b128 v[144:147], v238 offset:64
	s_waitcnt lgkmcnt(3)
	v_mfma_f32_32x32x16_bf16 v[48:63], v[148:151], v[112:115], 0
	ds_read_b128 v[148:151], v238 offset:6720
	s_waitcnt lgkmcnt(3)
	v_mfma_f32_32x32x16_bf16 v[32:47], v[152:155], v[116:119], v[32:47]
	ds_read_b128 v[152:155], v238 offset:96
	s_waitcnt lgkmcnt(3)
	v_mfma_f32_32x32x16_bf16 v[48:63], v[156:159], v[116:119], v[48:63]
	ds_read_b128 v[156:159], v238 offset:6752
	s_waitcnt lgkmcnt(3)
	v_mfma_f32_32x32x16_bf16 v[32:47], v[144:147], v[120:123], v[32:47]
	ds_read_b128 v[144:147], v238 offset:128
	s_waitcnt lgkmcnt(3)
	v_mfma_f32_32x32x16_bf16 v[48:63], v[148:151], v[120:123], v[48:63]
	ds_read_b128 v[148:151], v238 offset:6784
	s_waitcnt lgkmcnt(3)
	v_mfma_f32_32x32x16_bf16 v[32:47], v[152:155], v[124:127], v[32:47]
	ds_read_b128 v[152:155], v238 offset:160
	s_waitcnt lgkmcnt(3)
	v_mfma_f32_32x32x16_bf16 v[48:63], v[156:159], v[124:127], v[48:63]
	ds_read_b128 v[156:159], v238 offset:6816
	s_waitcnt lgkmcnt(3)
	v_mfma_f32_32x32x16_bf16 v[32:47], v[144:147], v[128:131], v[32:47]
	s_waitcnt lgkmcnt(2)
	v_mfma_f32_32x32x16_bf16 v[48:63], v[148:151], v[128:131], v[48:63]
	s_waitcnt lgkmcnt(1)
	v_mfma_f32_32x32x16_bf16 v[32:47], v[152:155], v[132:135], v[32:47]
	s_waitcnt lgkmcnt(0)
	v_mfma_f32_32x32x16_bf16 v[48:63], v[156:159], v[132:135], v[48:63]
	s_waitcnt lgkmcnt(0)
	s_barrier
	s_nop 7
	s_nop 3
	v_max3_f32 v223, v32, v33, v34
	v_max3_f32 v224, v40, v41, v42
	v_max3_f32 v225, v48, v49, v50
	v_max3_f32 v226, v56, v57, v58
	v_max3_f32 v223, v223, v35, v36
	v_max3_f32 v224, v224, v43, v44
	v_max3_f32 v225, v225, v51, v52
	v_max3_f32 v226, v226, v59, v60
	v_max3_f32 v223, v223, v37, v38
	v_max3_f32 v224, v224, v45, v46
	v_max3_f32 v225, v225, v53, v54
	v_max3_f32 v226, v226, v61, v62
	v_max_f32_e32 v223, v223, v39
	v_max_f32_e32 v224, v224, v47
	v_max_f32_e32 v225, v225, v55
	v_max_f32_e32 v226, v226, v63
	v_max3_f32 v222, v223, v224, v225
	v_max_f32_e32 v222, v222, v226
	v_mov_b32_e32 v227, v222
	s_nop 1
	v_permlane32_swap_b32_e32 v222, v227
	v_max_f32_e32 v222, v222, v227
	v_sub_f32_e32 v32, v32, v222
	v_sub_f32_e32 v33, v33, v222
	v_sub_f32_e32 v34, v34, v222
	v_sub_f32_e32 v35, v35, v222
	v_sub_f32_e32 v36, v36, v222
	v_sub_f32_e32 v37, v37, v222
	v_sub_f32_e32 v38, v38, v222
	v_sub_f32_e32 v39, v39, v222
	v_sub_f32_e32 v40, v40, v222
	v_sub_f32_e32 v41, v41, v222
	v_sub_f32_e32 v42, v42, v222
	v_sub_f32_e32 v43, v43, v222
	v_sub_f32_e32 v44, v44, v222
	v_sub_f32_e32 v45, v45, v222
	v_sub_f32_e32 v46, v46, v222
	v_sub_f32_e32 v47, v47, v222
	v_sub_f32_e32 v48, v48, v222
	v_sub_f32_e32 v49, v49, v222
	v_sub_f32_e32 v50, v50, v222
	v_sub_f32_e32 v51, v51, v222
	v_sub_f32_e32 v52, v52, v222
	v_sub_f32_e32 v53, v53, v222
	v_sub_f32_e32 v54, v54, v222
	v_sub_f32_e32 v55, v55, v222
	v_sub_f32_e32 v56, v56, v222
	v_sub_f32_e32 v57, v57, v222
	v_sub_f32_e32 v58, v58, v222
	v_sub_f32_e32 v59, v59, v222
	v_sub_f32_e32 v60, v60, v222
	v_sub_f32_e32 v61, v61, v222
	v_sub_f32_e32 v62, v62, v222
	v_sub_f32_e32 v63, v63, v222
	v_sub_f32_e32 v160, 0, v222
	v_sub_f32_e32 v161, 0, v222
	v_sub_f32_e32 v162, 0, v222
	v_sub_f32_e32 v163, 0, v222
	v_sub_f32_e32 v164, 0, v222
	v_sub_f32_e32 v165, 0, v222
	v_sub_f32_e32 v166, 0, v222
	v_sub_f32_e32 v167, 0, v222
	v_sub_f32_e32 v168, 0, v222
	v_sub_f32_e32 v169, 0, v222
	v_sub_f32_e32 v170, 0, v222
	v_sub_f32_e32 v171, 0, v222
	v_sub_f32_e32 v172, 0, v222
	v_sub_f32_e32 v173, 0, v222
	v_sub_f32_e32 v174, 0, v222
	v_sub_f32_e32 v175, 0, v222
	s_mov_b32 s69, 0
	s_mov_b32 s68, 0
	s_cmp_eq_u32 s74, 1
	s_cbranch_scc1 .Lat_safe_m
; template <int DQK>
; DI void attn_item(const bf16_t* __restrict__ Q, const bf16_t* __restrict__ Kp, const bf16_t* __restrict__ Vt, int q0, int nkeys,
;                   bf16_t* __restrict__ mix, int colbase, int b, char* smem) {
;     ...
;   for (int kt = 0; kt < nt; kt += 2) {
;     A_TILE(0)
;     A_WRITE(q, 1)
;     __syncthreads();
;     if (kt + 3 < nt) A_LOAD(q, (kt + 3) << 6)
;     A_TILE(1)
;     if (kt + 2 < nt) A_WRITE(p, 0)
;     __syncthreads();
;     if (kt + 4 < nt) A_LOAD(p, (kt + 4) << 6)
;   }
.Lat_floop_m:
	s_waitcnt vmcnt(0)
	ds_write_b128 v241, v[176:179] offset:0
	ds_write_b128 v242, v[180:183] offset:0
	ds_write_b128 v243, v[184:187] offset:0
	ds_write_b64 v244, v[212:213] offset:35328
	ds_write_b64 v244, v[214:215] offset:35336
	ds_write_b64 v245, v[216:217] offset:35328
	ds_write_b64 v245, v[218:219] offset:35336
	s_add_u32 s1, s68, 3
	s_add_u32 s10, s68, 2
	s_min_u32 s0, s1, 67
	s_mul_i32 s0, s0, 0x3000
	s_add_u32 s64, s60, s0
	s_addc_u32 s65, s61, 0
	s_min_u32 s0, s10, 67
	s_lshl_b32 s0, s0, 7
	s_add_u32 s66, s62, s0
	s_addc_u32 s67, s63, 0
	global_load_dwordx4 v[176:179], v246, s[64:65]
	global_load_dwordx4 v[180:183], v247, s[64:65]
	global_load_dwordx4 v[184:187], v248, s[64:65]
	global_load_dwordx4 v[212:215], v249, s[66:67]
	global_load_dwordx4 v[216:219], v250, s[66:67]
	ds_read_b128 v[144:147], v238 offset:13312
	ds_read_b128 v[148:151], v238 offset:19968
	ds_read_b128 v[152:155], v238 offset:13344
	ds_read_b128 v[156:159], v238 offset:20000
	v_exp_f32_e32 v32, v32
	v_exp_f32_e32 v33, v33
	s_waitcnt lgkmcnt(3)
	v_mfma_f32_32x32x16_bf16 v[64:79], v[144:147], v[112:115], v[160:175]
	ds_read_b128 v[144:147], v238 offset:13376
	v_exp_f32_e32 v34, v34
	v_exp_f32_e32 v35, v35
	s_waitcnt lgkmcnt(3)
	v_mfma_f32_32x32x16_bf16 v[80:95], v[148:151], v[112:115], v[160:175]
	ds_read_b128 v[148:151], v238 offset:20032
	v_exp_f32_e32 v36, v36
	v_exp_f32_e32 v37, v37
	s_waitcnt lgkmcnt(3)
	v_mfma_f32_32x32x16_bf16 v[64:79], v[152:155], v[116:119], v[64:79]
	ds_read_b128 v[152:155], v238 offset:13408
	v_exp_f32_e32 v38, v38
	v_exp_f32_e32 v39, v39
	s_waitcnt lgkmcnt(3)
	v_mfma_f32_32x32x16_bf16 v[80:95], v[156:159], v[116:119], v[80:95]
	ds_read_b128 v[156:159], v238 offset:20064
	v_exp_f32_e32 v40, v40
	v_exp_f32_e32 v41, v41
	s_waitcnt lgkmcnt(3)
	v_mfma_f32_32x32x16_bf16 v[64:79], v[144:147], v[120:123], v[64:79]
	ds_read_b128 v[144:147], v238 offset:13440
	v_exp_f32_e32 v42, v42
	v_exp_f32_e32 v43, v43
	s_waitcnt lgkmcnt(3)
	v_mfma_f32_32x32x16_bf16 v[80:95], v[148:151], v[120:123], v[80:95]
	ds_read_b128 v[148:151], v238 offset:20096
	v_exp_f32_e32 v44, v44
	v_exp_f32_e32 v45, v45
	s_waitcnt lgkmcnt(3)
	v_mfma_f32_32x32x16_bf16 v[64:79], v[152:155], v[124:127], v[64:79]
	ds_read_b128 v[152:155], v238 offset:13472
	v_exp_f32_e32 v46, v46
	v_exp_f32_e32 v47, v47
	s_waitcnt lgkmcnt(3)
	v_mfma_f32_32x32x16_bf16 v[80:95], v[156:159], v[124:127], v[80:95]
	ds_read_b128 v[156:159], v238 offset:20128
	v_exp_f32_e32 v48, v48
	v_exp_f32_e32 v49, v49
	s_waitcnt lgkmcnt(3)
	v_mfma_f32_32x32x16_bf16 v[64:79], v[144:147], v[128:131], v[64:79]
	v_exp_f32_e32 v50, v50
	v_exp_f32_e32 v51, v51
	s_waitcnt lgkmcnt(2)
	v_mfma_f32_32x32x16_bf16 v[80:95], v[148:151], v[128:131], v[80:95]
	v_exp_f32_e32 v52, v52
	v_exp_f32_e32 v53, v53
	s_waitcnt lgkmcnt(1)
	v_mfma_f32_32x32x16_bf16 v[64:79], v[152:155], v[132:135], v[64:79]
	v_exp_f32_e32 v54, v54
	v_exp_f32_e32 v55, v55
	s_waitcnt lgkmcnt(0)
	v_mfma_f32_32x32x16_bf16 v[80:95], v[156:159], v[132:135], v[80:95]
	v_exp_f32_e32 v56, v56
	v_exp_f32_e32 v57, v57
	v_exp_f32_e32 v58, v58
	v_exp_f32_e32 v59, v59
	v_exp_f32_e32 v60, v60
	v_exp_f32_e32 v61, v61
	v_exp_f32_e32 v62, v62
	v_exp_f32_e32 v63, v63
	v_add_u32_e32 v223, 0x6800, v239
	v_add_u32_e32 v224, 0x6800, v240
	ds_read2_b64 v[144:147], v223 offset0:0 offset1:2
	ds_read2_b64 v[148:151], v224 offset0:0 offset1:2
	ds_read2_b64 v[152:155], v223 offset0:4 offset1:6
	ds_read2_b64 v[156:159], v224 offset0:4 offset1:6
	v_cvt_pk_bf16_f32 v96, v32, v33
	v_cvt_pk_bf16_f32 v97, v34, v35
	v_cvt_pk_bf16_f32 v98, v36, v37
	v_cvt_pk_bf16_f32 v99, v38, v39
	v_add_f32_e32 v231, v32, v36
	v_add_f32_e32 v232, v33, v37
	v_add_f32_e32 v233, v34, v38
	v_add_f32_e32 v237, v35, v39
	s_waitcnt lgkmcnt(3)
	v_mfma_f32_32x32x16_bf16 v[0:15], v[144:147], v[96:99], v[0:15]
	ds_read2_b64 v[144:147], v223 offset0:8 offset1:10
	s_waitcnt lgkmcnt(3)
	v_mfma_f32_32x32x16_bf16 v[16:31], v[148:151], v[96:99], v[16:31]
	ds_read2_b64 v[148:151], v224 offset0:8 offset1:10
	v_cvt_pk_bf16_f32 v100, v40, v41
	v_cvt_pk_bf16_f32 v101, v42, v43
	v_cvt_pk_bf16_f32 v102, v44, v45
	v_cvt_pk_bf16_f32 v103, v46, v47
	v_add_f32_e32 v231, v231, v40
	v_add_f32_e32 v232, v232, v41
	v_add_f32_e32 v233, v233, v42
	v_add_f32_e32 v237, v237, v43
	v_add_f32_e32 v231, v231, v44
	v_add_f32_e32 v232, v232, v45
	v_add_f32_e32 v233, v233, v46
	v_add_f32_e32 v237, v237, v47
	s_waitcnt lgkmcnt(3)
	v_mfma_f32_32x32x16_bf16 v[0:15], v[152:155], v[100:103], v[0:15]
	ds_read2_b64 v[152:155], v223 offset0:12 offset1:14
	s_waitcnt lgkmcnt(3)
	v_mfma_f32_32x32x16_bf16 v[16:31], v[156:159], v[100:103], v[16:31]
	ds_read2_b64 v[156:159], v224 offset0:12 offset1:14
	v_cvt_pk_bf16_f32 v104, v48, v49
	v_cvt_pk_bf16_f32 v105, v50, v51
	v_cvt_pk_bf16_f32 v106, v52, v53
	v_cvt_pk_bf16_f32 v107, v54, v55
	v_add_f32_e32 v231, v231, v48
	v_add_f32_e32 v232, v232, v49
	v_add_f32_e32 v233, v233, v50
	v_add_f32_e32 v237, v237, v51
	v_add_f32_e32 v231, v231, v52
	v_add_f32_e32 v232, v232, v53
	v_add_f32_e32 v233, v233, v54
	v_add_f32_e32 v237, v237, v55
	s_waitcnt lgkmcnt(3)
	v_mfma_f32_32x32x16_bf16 v[0:15], v[144:147], v[104:107], v[0:15]
	s_waitcnt lgkmcnt(2)
	v_mfma_f32_32x32x16_bf16 v[16:31], v[148:151], v[104:107], v[16:31]
	v_cvt_pk_bf16_f32 v108, v56, v57
	v_cvt_pk_bf16_f32 v109, v58, v59
	v_cvt_pk_bf16_f32 v110, v60, v61
	v_cvt_pk_bf16_f32 v111, v62, v63
	v_add_f32_e32 v231, v231, v56
	v_add_f32_e32 v232, v232, v57
	v_add_f32_e32 v233, v233, v58
	v_add_f32_e32 v237, v237, v59
	v_add_f32_e32 v231, v231, v60
	v_add_f32_e32 v232, v232, v61
	v_add_f32_e32 v233, v233, v62
	v_add_f32_e32 v237, v237, v63
	s_waitcnt lgkmcnt(1)
	v_mfma_f32_32x32x16_bf16 v[0:15], v[152:155], v[108:111], v[0:15]
	s_waitcnt lgkmcnt(0)
	v_mfma_f32_32x32x16_bf16 v[16:31], v[156:159], v[108:111], v[16:31]
	v_add_f32_e32 v231, v231, v232
	v_add_f32_e32 v233, v233, v237
	v_add_f32_e32 v231, v231, v233
	v_add_f32_e32 v221, v221, v231
	s_add_u32 s68, s68, 1
	s_waitcnt lgkmcnt(0)
	s_barrier
; template <int DQK>
; DI void attn_item(const bf16_t* __restrict__ Q, const bf16_t* __restrict__ Kp, const bf16_t* __restrict__ Vt, int q0, int nkeys,
;                   bf16_t* __restrict__ mix, int colbase, int b, char* smem) {
;     ...
;   for (int kt = 0; kt < nt; kt += 2) {
;     A_TILE(0)
;     A_WRITE(q, 1)
;     __syncthreads();
;     if (kt + 3 < nt) A_LOAD(q, (kt + 3) << 6)
;     A_TILE(1)
;     if (kt + 2 < nt) A_WRITE(p, 0)
;     __syncthreads();
;     if (kt + 4 < nt) A_LOAD(p, (kt + 4) << 6)
;   }
	s_waitcnt vmcnt(0)
	ds_write_b128 v241, v[176:179] offset:13312
	ds_write_b128 v242, v[180:183] offset:13312
	ds_write_b128 v243, v[184:187] offset:13312
	ds_write_b64 v244, v[212:213] offset:26624
	ds_write_b64 v244, v[214:215] offset:26632
	ds_write_b64 v245, v[216:217] offset:26624
	ds_write_b64 v245, v[218:219] offset:26632
	s_add_u32 s1, s68, 3
	s_add_u32 s10, s68, 2
	s_min_u32 s0, s1, 67
	s_mul_i32 s0, s0, 0x3000
	s_add_u32 s64, s60, s0
	s_addc_u32 s65, s61, 0
	s_min_u32 s0, s10, 67
	s_lshl_b32 s0, s0, 7
	s_add_u32 s66, s62, s0
	s_addc_u32 s67, s63, 0
	global_load_dwordx4 v[176:179], v246, s[64:65]
	global_load_dwordx4 v[180:183], v247, s[64:65]
	global_load_dwordx4 v[184:187], v248, s[64:65]
	global_load_dwordx4 v[212:215], v249, s[66:67]
	global_load_dwordx4 v[216:219], v250, s[66:67]
	ds_read_b128 v[144:147], v238 offset:0
	ds_read_b128 v[148:151], v238 offset:6656
	ds_read_b128 v[152:155], v238 offset:32
	ds_read_b128 v[156:159], v238 offset:6688
	v_exp_f32_e32 v64, v64
	v_exp_f32_e32 v65, v65
	s_waitcnt lgkmcnt(3)
	v_mfma_f32_32x32x16_bf16 v[32:47], v[144:147], v[112:115], v[160:175]
	ds_read_b128 v[144:147], v238 offset:64
	v_exp_f32_e32 v66, v66
	v_exp_f32_e32 v67, v67
	s_waitcnt lgkmcnt(3)
	v_mfma_f32_32x32x16_bf16 v[48:63], v[148:151], v[112:115], v[160:175]
	ds_read_b128 v[148:151], v238 offset:6720
	v_exp_f32_e32 v68, v68
	v_exp_f32_e32 v69, v69
	s_waitcnt lgkmcnt(3)
	v_mfma_f32_32x32x16_bf16 v[32:47], v[152:155], v[116:119], v[32:47]
	ds_read_b128 v[152:155], v238 offset:96
	v_exp_f32_e32 v70, v70
	v_exp_f32_e32 v71, v71
	s_waitcnt lgkmcnt(3)
	v_mfma_f32_32x32x16_bf16 v[48:63], v[156:159], v[116:119], v[48:63]
	ds_read_b128 v[156:159], v238 offset:6752
	v_exp_f32_e32 v72, v72
	v_exp_f32_e32 v73, v73
	s_waitcnt lgkmcnt(3)
	v_mfma_f32_32x32x16_bf16 v[32:47], v[144:147], v[120:123], v[32:47]
	ds_read_b128 v[144:147], v238 offset:128
	v_exp_f32_e32 v74, v74
	v_exp_f32_e32 v75, v75
	s_waitcnt lgkmcnt(3)
	v_mfma_f32_32x32x16_bf16 v[48:63], v[148:151], v[120:123], v[48:63]
	ds_read_b128 v[148:151], v238 offset:6784
	v_exp_f32_e32 v76, v76
	v_exp_f32_e32 v77, v77
	s_waitcnt lgkmcnt(3)
	v_mfma_f32_32x32x16_bf16 v[32:47], v[152:155], v[124:127], v[32:47]
	ds_read_b128 v[152:155], v238 offset:160
	v_exp_f32_e32 v78, v78
	v_exp_f32_e32 v79, v79
	s_waitcnt lgkmcnt(3)
	v_mfma_f32_32x32x16_bf16 v[48:63], v[156:159], v[124:127], v[48:63]
	ds_read_b128 v[156:159], v238 offset:6816
	v_exp_f32_e32 v80, v80
	v_exp_f32_e32 v81, v81
	s_waitcnt lgkmcnt(3)
	v_mfma_f32_32x32x16_bf16 v[32:47], v[144:147], v[128:131], v[32:47]
	v_exp_f32_e32 v82, v82
	v_exp_f32_e32 v83, v83
	s_waitcnt lgkmcnt(2)
	v_mfma_f32_32x32x16_bf16 v[48:63], v[148:151], v[128:131], v[48:63]
	v_exp_f32_e32 v84, v84
	v_exp_f32_e32 v85, v85
	s_waitcnt lgkmcnt(1)
	v_mfma_f32_32x32x16_bf16 v[32:47], v[152:155], v[132:135], v[32:47]
	v_exp_f32_e32 v86, v86
	v_exp_f32_e32 v87, v87
	s_waitcnt lgkmcnt(0)
	v_mfma_f32_32x32x16_bf16 v[48:63], v[156:159], v[132:135], v[48:63]
	v_exp_f32_e32 v88, v88
	v_exp_f32_e32 v89, v89
	v_exp_f32_e32 v90, v90
	v_exp_f32_e32 v91, v91
	v_exp_f32_e32 v92, v92
	v_exp_f32_e32 v93, v93
	v_exp_f32_e32 v94, v94
	v_exp_f32_e32 v95, v95
	v_add_u32_e32 v223, 0x8a00, v239
	v_add_u32_e32 v224, 0x8a00, v240
	ds_read2_b64 v[144:147], v223 offset0:0 offset1:2
	ds_read2_b64 v[148:151], v224 offset0:0 offset1:2
	ds_read2_b64 v[152:155], v223 offset0:4 offset1:6
	ds_read2_b64 v[156:159], v224 offset0:4 offset1:6
	v_cvt_pk_bf16_f32 v96, v64, v65
	v_cvt_pk_bf16_f32 v97, v66, v67
	v_cvt_pk_bf16_f32 v98, v68, v69
	v_cvt_pk_bf16_f32 v99, v70, v71
	v_add_f32_e32 v231, v64, v68
	v_add_f32_e32 v232, v65, v69
	v_add_f32_e32 v233, v66, v70
	v_add_f32_e32 v237, v67, v71
	s_waitcnt lgkmcnt(3)
	v_mfma_f32_32x32x16_bf16 v[0:15], v[144:147], v[96:99], v[0:15]
	ds_read2_b64 v[144:147], v223 offset0:8 offset1:10
	s_waitcnt lgkmcnt(3)
	v_mfma_f32_32x32x16_bf16 v[16:31], v[148:151], v[96:99], v[16:31]
	ds_read2_b64 v[148:151], v224 offset0:8 offset1:10
	v_cvt_pk_bf16_f32 v100, v72, v73
	v_cvt_pk_bf16_f32 v101, v74, v75
	v_cvt_pk_bf16_f32 v102, v76, v77
	v_cvt_pk_bf16_f32 v103, v78, v79
	v_add_f32_e32 v231, v231, v72
	v_add_f32_e32 v232, v232, v73
	v_add_f32_e32 v233, v233, v74
	v_add_f32_e32 v237, v237, v75
	v_add_f32_e32 v231, v231, v76
	v_add_f32_e32 v232, v232, v77
	v_add_f32_e32 v233, v233, v78
	v_add_f32_e32 v237, v237, v79
	s_waitcnt lgkmcnt(3)
	v_mfma_f32_32x32x16_bf16 v[0:15], v[152:155], v[100:103], v[0:15]
	ds_read2_b64 v[152:155], v223 offset0:12 offset1:14
	s_waitcnt lgkmcnt(3)
	v_mfma_f32_32x32x16_bf16 v[16:31], v[156:159], v[100:103], v[16:31]
	ds_read2_b64 v[156:159], v224 offset0:12 offset1:14
	v_cvt_pk_bf16_f32 v104, v80, v81
	v_cvt_pk_bf16_f32 v105, v82, v83
	v_cvt_pk_bf16_f32 v106, v84, v85
	v_cvt_pk_bf16_f32 v107, v86, v87
	v_add_f32_e32 v231, v231, v80
	v_add_f32_e32 v232, v232, v81
	v_add_f32_e32 v233, v233, v82
	v_add_f32_e32 v237, v237, v83
	v_add_f32_e32 v231, v231, v84
	v_add_f32_e32 v232, v232, v85
	v_add_f32_e32 v233, v233, v86
	v_add_f32_e32 v237, v237, v87
	s_waitcnt lgkmcnt(3)
	v_mfma_f32_32x32x16_bf16 v[0:15], v[144:147], v[104:107], v[0:15]
	s_waitcnt lgkmcnt(2)
	v_mfma_f32_32x32x16_bf16 v[16:31], v[148:151], v[104:107], v[16:31]
	v_cvt_pk_bf16_f32 v108, v88, v89
	v_cvt_pk_bf16_f32 v109, v90, v91
	v_cvt_pk_bf16_f32 v110, v92, v93
	v_cvt_pk_bf16_f32 v111, v94, v95
	v_add_f32_e32 v231, v231, v88
	v_add_f32_e32 v232, v232, v89
	v_add_f32_e32 v233, v233, v90
	v_add_f32_e32 v237, v237, v91
	v_add_f32_e32 v231, v231, v92
	v_add_f32_e32 v232, v232, v93
	v_add_f32_e32 v233, v233, v94
	v_add_f32_e32 v237, v237, v95
	s_waitcnt lgkmcnt(1)
	v_mfma_f32_32x32x16_bf16 v[0:15], v[152:155], v[108:111], v[0:15]
	s_waitcnt lgkmcnt(0)
	v_mfma_f32_32x32x16_bf16 v[16:31], v[156:159], v[108:111], v[16:31]
	v_add_f32_e32 v231, v231, v232
	v_add_f32_e32 v233, v233, v237
	v_add_f32_e32 v231, v231, v233
	v_add_f32_e32 v221, v221, v231
	s_add_u32 s68, s68, 1
	s_waitcnt lgkmcnt(0)
	s_barrier
; DI float xhalf_sum(float x) { auto r = __builtin_amdgcn_permlane32_swap(__float_as_uint(x), __float_as_uint(x), false, false); return __uint_as_float(r[0]) + __uint_as_float(r[1]); }
; template <int DQK>
; DI void attn_item(const bf16_t* __restrict__ Q, const bf16_t* __restrict__ Kp, const bf16_t* __restrict__ Vt, int q0, int nkeys,
;                   bf16_t* __restrict__ mix, int colbase, int b, char* smem) {
;     ...
;   const int nt = nkeys >> 6;
;   A_LOAD(p, 0)
;   A_LOAD(q, 64)
;   A_WRITE(p, 0)
;   __syncthreads();
;   if (nt > 2) A_LOAD(p, 128)
;   for (int kt = 0; kt < nt; kt += 2) {
;     A_TILE(0)
;     A_WRITE(q, 1)
;     __syncthreads();
;     if (kt + 3 < nt) A_LOAD(q, (kt + 3) << 6)
;     A_TILE(1)
;     if (kt + 2 < nt) A_WRITE(p, 0)
;     __syncthreads();
;     if (kt + 4 < nt) A_LOAD(p, (kt + 4) << 6)
;   }
;     ...
;   l = xhalf_sum(l);
	s_cmp_lt_u32 s68, 68
	s_cbranch_scc1 .Lat_floop_m
	s_nop 7
	s_nop 7
	v_mov_b32_e32 v223, 0
	v_fmac_f32_e32 v223, 0, v0
	v_fmac_f32_e32 v223, 0, v1
	v_fmac_f32_e32 v223, 0, v2
	v_fmac_f32_e32 v223, 0, v3
	v_fmac_f32_e32 v223, 0, v4
	v_fmac_f32_e32 v223, 0, v5
	v_fmac_f32_e32 v223, 0, v6
	v_fmac_f32_e32 v223, 0, v7
	v_fmac_f32_e32 v223, 0, v8
	v_fmac_f32_e32 v223, 0, v9
	v_fmac_f32_e32 v223, 0, v10
	v_fmac_f32_e32 v223, 0, v11
	v_fmac_f32_e32 v223, 0, v12
	v_fmac_f32_e32 v223, 0, v13
	v_fmac_f32_e32 v223, 0, v14
	v_fmac_f32_e32 v223, 0, v15
	v_fmac_f32_e32 v223, 0, v16
	v_fmac_f32_e32 v223, 0, v17
	v_fmac_f32_e32 v223, 0, v18
	v_fmac_f32_e32 v223, 0, v19
	v_fmac_f32_e32 v223, 0, v20
	v_fmac_f32_e32 v223, 0, v21
	v_fmac_f32_e32 v223, 0, v22
	v_fmac_f32_e32 v223, 0, v23
	v_fmac_f32_e32 v223, 0, v24
	v_fmac_f32_e32 v223, 0, v25
	v_fmac_f32_e32 v223, 0, v26
	v_fmac_f32_e32 v223, 0, v27
	v_fmac_f32_e32 v223, 0, v28
	v_fmac_f32_e32 v223, 0, v29
	v_fmac_f32_e32 v223, 0, v30
	v_fmac_f32_e32 v223, 0, v31
	v_mov_b32_e32 v224, 0x71800000
	v_cmp_neq_f32_e32 vcc, 0, v223
	s_mov_b64 s[44:45], vcc
	v_cmp_nlt_f32_e32 vcc, v221, v224
	s_or_b64 vcc, vcc, s[44:45]
	s_cmp_lg_u64 vcc, 0
	s_cselect_b32 s0, 1, 0
	v_mov_b32_e32 v225, s0
	s_lshl_b32 s1, s57, 2
	s_add_u32 s1, s1, 0x10000
	v_mov_b32_e32 v226, s1
	v_mov_b32_e32 v227, 0x10000
	ds_write_b32 v226, v225
	s_waitcnt lgkmcnt(0)
	s_barrier
	ds_read_b128 v[144:147], v227
	s_waitcnt lgkmcnt(0)
	v_or3_b32 v225, v144, v145, v146
	v_or_b32_e32 v225, v225, v147
	s_nop 0
	v_readfirstlane_b32 s0, v225
	s_nop 3
	s_cmp_eq_u32 s0, 0
	s_cbranch_scc1 .Lat_epi_m
	s_mov_b32 s74, 1
	s_branch .Lat_redo_m
.Lat_safe_m:
.Lat_loop_m:
	s_waitcnt vmcnt(0)
	ds_write_b128 v241, v[176:179] offset:0
	ds_write_b128 v242, v[180:183] offset:0
	ds_write_b128 v243, v[184:187] offset:0
	ds_write_b64 v244, v[212:213] offset:35328
	ds_write_b64 v244, v[214:215] offset:35336
	ds_write_b64 v245, v[216:217] offset:35328
	ds_write_b64 v245, v[218:219] offset:35336
	s_add_u32 s1, s68, 3
	s_add_u32 s10, s68, 2
	s_min_u32 s0, s1, 67
	s_mul_i32 s0, s0, 0x3000
	s_add_u32 s64, s60, s0
	s_addc_u32 s65, s61, 0
	s_min_u32 s0, s10, 67
	s_lshl_b32 s0, s0, 7
	s_add_u32 s66, s62, s0
	s_addc_u32 s67, s63, 0
	global_load_dwordx4 v[176:179], v246, s[64:65]
	global_load_dwordx4 v[180:183], v247, s[64:65]
	global_load_dwordx4 v[184:187], v248, s[64:65]
	global_load_dwordx4 v[212:215], v249, s[66:67]
	global_load_dwordx4 v[216:219], v250, s[66:67]
	s_cmp_eq_u32 s69, 0
	s_cbranch_scc1 .Lat_nopend_8
	v_sub_f32_e32 v32, v32, v220
	v_sub_f32_e32 v33, v33, v220
	v_sub_f32_e32 v34, v34, v220
	v_sub_f32_e32 v35, v35, v220
	v_sub_f32_e32 v36, v36, v220
	v_sub_f32_e32 v37, v37, v220
	v_sub_f32_e32 v38, v38, v220
	v_sub_f32_e32 v39, v39, v220
	v_sub_f32_e32 v40, v40, v220
	v_sub_f32_e32 v41, v41, v220
	v_sub_f32_e32 v42, v42, v220
	v_sub_f32_e32 v43, v43, v220
	v_sub_f32_e32 v44, v44, v220
	v_sub_f32_e32 v45, v45, v220
	v_sub_f32_e32 v46, v46, v220
	v_sub_f32_e32 v47, v47, v220
	v_sub_f32_e32 v48, v48, v220
	v_sub_f32_e32 v49, v49, v220
	v_sub_f32_e32 v50, v50, v220
	v_sub_f32_e32 v51, v51, v220
	v_sub_f32_e32 v52, v52, v220
	v_sub_f32_e32 v53, v53, v220
	v_sub_f32_e32 v54, v54, v220
	v_sub_f32_e32 v55, v55, v220
	v_sub_f32_e32 v56, v56, v220
	v_sub_f32_e32 v57, v57, v220
	v_sub_f32_e32 v58, v58, v220
	v_sub_f32_e32 v59, v59, v220
	v_sub_f32_e32 v60, v60, v220
	v_sub_f32_e32 v61, v61, v220
	v_sub_f32_e32 v62, v62, v220
	v_sub_f32_e32 v63, v63, v220
	s_mov_b32 s69, 0

; DI unsigned pack2(float lo, float hi) { f32x2_t v = {lo, hi}; bf16x2_t r = __builtin_convertvector(v, bf16x2_t); return __builtin_bit_cast(unsigned, r); }
; DI float xhalf_sum(float x) { auto r = __builtin_amdgcn_permlane32_swap(__float_as_uint(x), __float_as_uint(x), false, false); return __uint_as_float(r[0]) + __uint_as_float(r[1]); }
; template <int DQK>
; DI void attn_item(const bf16_t* __restrict__ Q, const bf16_t* __restrict__ Kp, const bf16_t* __restrict__ Vt, int q0, int nkeys,
;                   bf16_t* __restrict__ mix, int colbase, int b, char* smem) {
;     ...
;   l = xhalf_sum(l);
;   const float inv = 1.0f / l;
;   const int kp = q0 + wave * 32 + r;
;   bf16_t* orow = mix + (size_t)row_of(b, kp) * D + colbase;
; #pragma unroll
;   for (int g = 0; g < 4; ++g) {
;     uint2 w0, w1;
;     w0.x = pack2(o0[4 * g] * inv, o0[4 * g + 1] * inv); w0.y = pack2(o0[4 * g + 2] * inv, o0[4 * g + 3] * inv);
;     w1.x = pack2(o1[4 * g] * inv, o1[4 * g + 1] * inv); w1.y = pack2(o1[4 * g + 2] * inv, o1[4 * g + 3] * inv);
;     *(uint2*)(orow + 8 * g + 4 * h) = w0;
;     *(uint2*)(orow + 32 + 8 * g + 4 * h) = w1;
;   }
.Lat_epi_m:
	s_nop 7
	v_mov_b32_e32 v223, v221
	s_nop 1
	v_permlane32_swap_b32_e32 v221, v223
	v_add_f32_e32 v221, v221, v223
	v_rcp_f32_e32 v224, v221
	v_add_u32_e32 v226, 0x220000, v252
	s_nop 0
	v_mul_f32_e32 v96, v0, v224
	v_mul_f32_e32 v97, v1, v224
	v_mul_f32_e32 v98, v2, v224
	v_mul_f32_e32 v99, v3, v224
	v_cvt_pk_bf16_f32 v144, v96, v97
	v_cvt_pk_bf16_f32 v145, v98, v99
	global_store_dwordx2 v252, v[144:145], s[72:73] offset:0
	v_mul_f32_e32 v96, v16, v224
	v_mul_f32_e32 v97, v17, v224
	v_mul_f32_e32 v98, v18, v224
	v_mul_f32_e32 v99, v19, v224
	v_cvt_pk_bf16_f32 v146, v96, v97
	v_cvt_pk_bf16_f32 v147, v98, v99
	global_store_dwordx2 v226, v[146:147], s[72:73] offset:0
	v_mul_f32_e32 v96, v4, v224
	v_mul_f32_e32 v97, v5, v224
	v_mul_f32_e32 v98, v6, v224
	v_mul_f32_e32 v99, v7, v224
	v_cvt_pk_bf16_f32 v148, v96, v97
	v_cvt_pk_bf16_f32 v149, v98, v99
	global_store_dwordx2 v252, v[148:149], s[72:73] offset:16
	v_mul_f32_e32 v96, v20, v224
	v_mul_f32_e32 v97, v21, v224
	v_mul_f32_e32 v98, v22, v224
	v_mul_f32_e32 v99, v23, v224
	v_cvt_pk_bf16_f32 v150, v96, v97
	v_cvt_pk_bf16_f32 v151, v98, v99
	global_store_dwordx2 v226, v[150:151], s[72:73] offset:16
	v_mul_f32_e32 v96, v8, v224
	v_mul_f32_e32 v97, v9, v224
	v_mul_f32_e32 v98, v10, v224
	v_mul_f32_e32 v99, v11, v224
	v_cvt_pk_bf16_f32 v152, v96, v97
	v_cvt_pk_bf16_f32 v153, v98, v99
	global_store_dwordx2 v252, v[152:153], s[72:73] offset:32
	v_mul_f32_e32 v96, v24, v224
	v_mul_f32_e32 v97, v25, v224
	v_mul_f32_e32 v98, v26, v224
	v_mul_f32_e32 v99, v27, v224
	v_cvt_pk_bf16_f32 v154, v96, v97
	v_cvt_pk_bf16_f32 v155, v98, v99
	global_store_dwordx2 v226, v[154:155], s[72:73] offset:32
	v_mul_f32_e32 v96, v12, v224
	v_mul_f32_e32 v97, v13, v224
	v_mul_f32_e32 v98, v14, v224
	v_mul_f32_e32 v99, v15, v224
	v_cvt_pk_bf16_f32 v156, v96, v97
	v_cvt_pk_bf16_f32 v157, v98, v99
	global_store_dwordx2 v252, v[156:157], s[72:73] offset:48
	v_mul_f32_e32 v96, v28, v224
	v_mul_f32_e32 v97, v29, v224
	v_mul_f32_e32 v98, v30, v224
	v_mul_f32_e32 v99, v31, v224
	v_cvt_pk_bf16_f32 v158, v96, v97
	v_cvt_pk_bf16_f32 v159, v98, v99
	global_store_dwordx2 v226, v[158:159], s[72:73] offset:48
